# MFMA order: dependent accumulate chains (k0,k1 back to back) in K-loop
# speedup vs baseline: 1.0014x; 1.0014x over previous
.LBB0_230:
	s_add_i32 s4, s5, 2
	s_add_u32 s62, s76, s12
	s_addc_u32 s78, s77, s13
	s_add_u32 s80, s74, s12
	s_addc_u32 s81, s75, s13
	s_add_i32 s82, 0, 0x10000
	s_cmp_eq_u32 s97, s5
	s_cselect_b32 s79, s71, s78
	s_cselect_b32 s78, s70, s62
	v_add_u32_e32 v0, s82, v188
	s_cselect_b32 s81, s73, s81
	s_cselect_b32 s80, s72, s80
	s_add_i32 s5, 0, 0x14000
	ds_read_b128 v[134:137], v0
	ds_read_b128 v[158:161], v0 offset:1024
	ds_read_b128 v[162:165], v0 offset:2048
	ds_read_b128 v[166:169], v0 offset:3072
	v_add_u32_e32 v0, s5, v188
	ds_read_b128 v[198:201], v0
	ds_read_b128 v[202:205], v0 offset:1024
	ds_read_b128 v[206:209], v0 offset:2048
	ds_read_b128 v[210:213], v0 offset:3072
	v_lshl_add_u64 v[138:139], s[76:77], 0, v[132:133]
	s_add_i32 m0, s90, 0xc000
	ds_read_b128 v[214:217], v192
	ds_read_b128 v[218:221], v192 offset:1024
	ds_read_b128 v[222:225], v192 offset:2048
	ds_read_b128 v[226:229], v192 offset:3072
	ds_read_b128 v[230:233], v192 offset:4096
	ds_read_b128 v[234:237], v192 offset:5120
	ds_read_b128 v[238:241], v192 offset:6144
	ds_read_b128 v[242:245], v192 offset:7168
	global_load_lds_dwordx4 v[138:139], off
	v_lshl_add_u64 v[138:139], s[76:77], 0, v[2:3]
	s_add_i32 m0, s90, 0xe000
	s_nop 0
	global_load_lds_dwordx4 v[138:139], off
	s_waitcnt vmcnt(8)
	s_waitcnt lgkmcnt(0)
	s_barrier
	s_setprio 1
	s_waitcnt lgkmcnt(0)
	v_mfma_f32_16x16x32_bf16 v[4:7], v[134:137], v[214:217], v[4:7]
	v_mfma_f32_16x16x32_bf16 v[4:7], v[158:161], v[218:221], v[4:7]
	v_mfma_f32_16x16x32_bf16 v[8:11], v[162:165], v[214:217], v[8:11]
	v_mfma_f32_16x16x32_bf16 v[8:11], v[166:169], v[218:221], v[8:11]
	v_mfma_f32_16x16x32_bf16 v[20:23], v[134:137], v[222:225], v[20:23]
	v_mfma_f32_16x16x32_bf16 v[20:23], v[158:161], v[226:229], v[20:23]
	v_mfma_f32_16x16x32_bf16 v[24:27], v[162:165], v[222:225], v[24:27]
	v_mfma_f32_16x16x32_bf16 v[24:27], v[166:169], v[226:229], v[24:27]
	v_mfma_f32_16x16x32_bf16 v[36:39], v[134:137], v[230:233], v[36:39]
	v_mfma_f32_16x16x32_bf16 v[36:39], v[158:161], v[234:237], v[36:39]
	v_mfma_f32_16x16x32_bf16 v[40:43], v[162:165], v[230:233], v[40:43]
	v_mfma_f32_16x16x32_bf16 v[40:43], v[166:169], v[234:237], v[40:43]
	v_mfma_f32_16x16x32_bf16 v[52:55], v[134:137], v[238:241], v[52:55]
	v_mfma_f32_16x16x32_bf16 v[52:55], v[158:161], v[242:245], v[52:55]
	v_mfma_f32_16x16x32_bf16 v[56:59], v[162:165], v[238:241], v[56:59]
	v_mfma_f32_16x16x32_bf16 v[56:59], v[166:169], v[242:245], v[56:59]
	s_setprio 0
	s_setprio 1
	v_mfma_f32_16x16x32_bf16 v[12:15], v[198:201], v[214:217], v[12:15]
	v_mfma_f32_16x16x32_bf16 v[12:15], v[202:205], v[218:221], v[12:15]
	v_mfma_f32_16x16x32_bf16 v[16:19], v[206:209], v[214:217], v[16:19]
	v_mfma_f32_16x16x32_bf16 v[16:19], v[210:213], v[218:221], v[16:19]
	v_mfma_f32_16x16x32_bf16 v[28:31], v[198:201], v[222:225], v[28:31]
	v_mfma_f32_16x16x32_bf16 v[28:31], v[202:205], v[226:229], v[28:31]
	v_mfma_f32_16x16x32_bf16 v[32:35], v[206:209], v[222:225], v[32:35]
	v_mfma_f32_16x16x32_bf16 v[32:35], v[210:213], v[226:229], v[32:35]
	v_mfma_f32_16x16x32_bf16 v[44:47], v[198:201], v[230:233], v[44:47]
	v_mfma_f32_16x16x32_bf16 v[44:47], v[202:205], v[234:237], v[44:47]
	v_mfma_f32_16x16x32_bf16 v[48:51], v[206:209], v[230:233], v[48:51]
	v_mfma_f32_16x16x32_bf16 v[48:51], v[210:213], v[234:237], v[48:51]
	v_mfma_f32_16x16x32_bf16 v[60:63], v[198:201], v[238:241], v[60:63]
	v_mfma_f32_16x16x32_bf16 v[60:63], v[202:205], v[242:245], v[60:63]
	v_mfma_f32_16x16x32_bf16 v[64:67], v[206:209], v[238:241], v[64:67]
	v_mfma_f32_16x16x32_bf16 v[64:67], v[210:213], v[242:245], v[64:67]
	s_setprio 0
	s_barrier
	s_add_i32 s62, s82, s89
	v_lshl_add_u64 v[138:139], s[80:81], 0, v[144:145]
	s_mov_b32 m0, s62
	ds_read_b128 v[214:217], v192 offset:16384
	ds_read_b128 v[218:221], v192 offset:17408
	ds_read_b128 v[222:225], v192 offset:18432
	ds_read_b128 v[226:229], v192 offset:19456
	ds_read_b128 v[230:233], v192 offset:20480
	ds_read_b128 v[234:237], v192 offset:21504
	ds_read_b128 v[238:241], v192 offset:22528
	ds_read_b128 v[242:245], v192 offset:23552
	global_load_lds_dwordx4 v[138:139], off
	s_add_i32 m0, s62, 0x2000
	v_lshl_add_u64 v[194:195], s[80:81], 0, v[148:149]
	s_add_u32 s80, s80, s54
	s_addc_u32 s81, s81, s55
	s_add_i32 s5, s5, s89
	global_load_lds_dwordx4 v[194:195], off
	v_lshl_add_u64 v[246:247], s[80:81], 0, v[144:145]
	s_mov_b32 m0, s5
	v_lshl_add_u64 v[248:249], s[80:81], 0, v[148:149]
	global_load_lds_dwordx4 v[246:247], off
	s_add_i32 m0, s5, 0x2000
	v_lshl_add_u64 v[250:251], s[78:79], 0, v[142:143]
	global_load_lds_dwordx4 v[248:249], off
	s_mov_b32 m0, s90
	v_lshl_add_u64 v[180:181], s[78:79], 0, v[146:147]
	global_load_lds_dwordx4 v[250:251], off
	s_mov_b32 m0, s91
	s_nop 0
	global_load_lds_dwordx4 v[180:181], off
	s_waitcnt vmcnt(8)
	s_waitcnt lgkmcnt(0)
	s_barrier
	s_setprio 1
	s_waitcnt lgkmcnt(0)
	v_mfma_f32_16x16x32_bf16 v[68:71], v[134:137], v[214:217], v[68:71]
	v_mfma_f32_16x16x32_bf16 v[68:71], v[158:161], v[218:221], v[68:71]
	v_mfma_f32_16x16x32_bf16 v[72:75], v[162:165], v[214:217], v[72:75]
	v_mfma_f32_16x16x32_bf16 v[72:75], v[166:169], v[218:221], v[72:75]
	v_mfma_f32_16x16x32_bf16 v[84:87], v[134:137], v[222:225], v[84:87]
	v_mfma_f32_16x16x32_bf16 v[84:87], v[158:161], v[226:229], v[84:87]
	v_mfma_f32_16x16x32_bf16 v[88:91], v[162:165], v[222:225], v[88:91]
	v_mfma_f32_16x16x32_bf16 v[88:91], v[166:169], v[226:229], v[88:91]
	v_mfma_f32_16x16x32_bf16 v[100:103], v[134:137], v[230:233], v[100:103]
	v_mfma_f32_16x16x32_bf16 v[100:103], v[158:161], v[234:237], v[100:103]
	v_mfma_f32_16x16x32_bf16 v[104:107], v[162:165], v[230:233], v[104:107]
	v_mfma_f32_16x16x32_bf16 v[104:107], v[166:169], v[234:237], v[104:107]
	v_mfma_f32_16x16x32_bf16 v[116:119], v[134:137], v[238:241], v[116:119]
	v_mfma_f32_16x16x32_bf16 v[116:119], v[158:161], v[242:245], v[116:119]
	v_mfma_f32_16x16x32_bf16 v[120:123], v[162:165], v[238:241], v[120:123]
	v_mfma_f32_16x16x32_bf16 v[120:123], v[166:169], v[242:245], v[120:123]
	s_setprio 0
	s_setprio 1
	v_mfma_f32_16x16x32_bf16 v[76:79], v[198:201], v[214:217], v[76:79]
	v_mfma_f32_16x16x32_bf16 v[76:79], v[202:205], v[218:221], v[76:79]
	v_mfma_f32_16x16x32_bf16 v[80:83], v[206:209], v[214:217], v[80:83]
	v_mfma_f32_16x16x32_bf16 v[80:83], v[210:213], v[218:221], v[80:83]
	v_mfma_f32_16x16x32_bf16 v[92:95], v[198:201], v[222:225], v[92:95]
	v_mfma_f32_16x16x32_bf16 v[92:95], v[202:205], v[226:229], v[92:95]
	v_mfma_f32_16x16x32_bf16 v[96:99], v[206:209], v[222:225], v[96:99]
	v_mfma_f32_16x16x32_bf16 v[96:99], v[210:213], v[226:229], v[96:99]
	v_mfma_f32_16x16x32_bf16 v[108:111], v[198:201], v[230:233], v[108:111]
	v_mfma_f32_16x16x32_bf16 v[108:111], v[202:205], v[234:237], v[108:111]
	v_mfma_f32_16x16x32_bf16 v[112:115], v[206:209], v[230:233], v[112:115]
	v_mfma_f32_16x16x32_bf16 v[112:115], v[210:213], v[234:237], v[112:115]
	v_mfma_f32_16x16x32_bf16 v[124:127], v[198:201], v[238:241], v[124:127]
	v_mfma_f32_16x16x32_bf16 v[124:127], v[202:205], v[242:245], v[124:127]
	v_mfma_f32_16x16x32_bf16 v[128:131], v[206:209], v[238:241], v[128:131]
	v_mfma_f32_16x16x32_bf16 v[128:131], v[210:213], v[242:245], v[128:131]
	s_setprio 0
	s_barrier
	s_add_i32 s5, 0, 0x18000
	v_add_u32_e32 v0, s5, v188
	s_add_i32 s62, 0, 0x1c000
	ds_read_b128 v[134:137], v0
	ds_read_b128 v[158:161], v0 offset:1024
	ds_read_b128 v[162:165], v0 offset:2048
	ds_read_b128 v[166:169], v0 offset:3072
	v_add_u32_e32 v0, s62, v188
	ds_read_b128 v[198:201], v0
	ds_read_b128 v[202:205], v0 offset:1024
	ds_read_b128 v[206:209], v0 offset:2048
	ds_read_b128 v[210:213], v0 offset:3072
	s_add_u32 s78, s78, s54
	s_addc_u32 s79, s79, s55
	s_mov_b32 m0, s92
	v_lshl_add_u64 v[182:183], s[78:79], 0, v[142:143]
	ds_read_b128 v[214:217], v192 offset:32768
	ds_read_b128 v[218:221], v192 offset:33792
	ds_read_b128 v[222:225], v192 offset:34816
	ds_read_b128 v[226:229], v192 offset:35840
	ds_read_b128 v[230:233], v192 offset:36864
	ds_read_b128 v[234:237], v192 offset:37888
	ds_read_b128 v[238:241], v192 offset:38912
	ds_read_b128 v[242:245], v192 offset:39936
	global_load_lds_dwordx4 v[182:183], off
	v_lshl_add_u64 v[182:183], s[78:79], 0, v[146:147]
	s_mov_b32 m0, s93
	s_nop 0
	global_load_lds_dwordx4 v[182:183], off
	s_waitcnt vmcnt(8)
	s_waitcnt lgkmcnt(0)
	s_barrier
	s_setprio 1
	s_waitcnt lgkmcnt(0)
	v_mfma_f32_16x16x32_bf16 v[4:7], v[134:137], v[214:217], v[4:7]
	v_mfma_f32_16x16x32_bf16 v[4:7], v[158:161], v[218:221], v[4:7]
	v_mfma_f32_16x16x32_bf16 v[8:11], v[162:165], v[214:217], v[8:11]
	v_mfma_f32_16x16x32_bf16 v[8:11], v[166:169], v[218:221], v[8:11]
	v_mfma_f32_16x16x32_bf16 v[20:23], v[134:137], v[222:225], v[20:23]
	v_mfma_f32_16x16x32_bf16 v[20:23], v[158:161], v[226:229], v[20:23]
	v_mfma_f32_16x16x32_bf16 v[24:27], v[162:165], v[222:225], v[24:27]
	v_mfma_f32_16x16x32_bf16 v[24:27], v[166:169], v[226:229], v[24:27]
	v_mfma_f32_16x16x32_bf16 v[36:39], v[134:137], v[230:233], v[36:39]
	v_mfma_f32_16x16x32_bf16 v[36:39], v[158:161], v[234:237], v[36:39]
	v_mfma_f32_16x16x32_bf16 v[40:43], v[162:165], v[230:233], v[40:43]
	v_mfma_f32_16x16x32_bf16 v[40:43], v[166:169], v[234:237], v[40:43]
	v_mfma_f32_16x16x32_bf16 v[52:55], v[134:137], v[238:241], v[52:55]
	v_mfma_f32_16x16x32_bf16 v[52:55], v[158:161], v[242:245], v[52:55]
	v_mfma_f32_16x16x32_bf16 v[56:59], v[162:165], v[238:241], v[56:59]
	v_mfma_f32_16x16x32_bf16 v[56:59], v[166:169], v[242:245], v[56:59]
	s_setprio 0
	s_setprio 1
	v_mfma_f32_16x16x32_bf16 v[12:15], v[198:201], v[214:217], v[12:15]
	v_mfma_f32_16x16x32_bf16 v[12:15], v[202:205], v[218:221], v[12:15]
	v_mfma_f32_16x16x32_bf16 v[16:19], v[206:209], v[214:217], v[16:19]
	v_mfma_f32_16x16x32_bf16 v[16:19], v[210:213], v[218:221], v[16:19]
	v_mfma_f32_16x16x32_bf16 v[28:31], v[198:201], v[222:225], v[28:31]
	v_mfma_f32_16x16x32_bf16 v[28:31], v[202:205], v[226:229], v[28:31]
	v_mfma_f32_16x16x32_bf16 v[32:35], v[206:209], v[222:225], v[32:35]
	v_mfma_f32_16x16x32_bf16 v[32:35], v[210:213], v[226:229], v[32:35]
	v_mfma_f32_16x16x32_bf16 v[44:47], v[198:201], v[230:233], v[44:47]
	v_mfma_f32_16x16x32_bf16 v[44:47], v[202:205], v[234:237], v[44:47]
	v_mfma_f32_16x16x32_bf16 v[48:51], v[206:209], v[230:233], v[48:51]
	v_mfma_f32_16x16x32_bf16 v[48:51], v[210:213], v[234:237], v[48:51]
	v_mfma_f32_16x16x32_bf16 v[60:63], v[198:201], v[238:241], v[60:63]
	v_mfma_f32_16x16x32_bf16 v[60:63], v[202:205], v[242:245], v[60:63]
	v_mfma_f32_16x16x32_bf16 v[64:67], v[206:209], v[238:241], v[64:67]
	v_mfma_f32_16x16x32_bf16 v[64:67], v[210:213], v[242:245], v[64:67]
	s_setprio 0
	s_barrier
	s_add_i32 s5, s5, s89
	v_lshl_add_u64 v[138:139], v[138:139], 0, s[56:57]
	s_mov_b32 m0, s5
	ds_read_b128 v[214:217], v192 offset:49152
	ds_read_b128 v[218:221], v192 offset:50176
	ds_read_b128 v[222:225], v192 offset:51200
	ds_read_b128 v[226:229], v192 offset:52224
	ds_read_b128 v[230:233], v192 offset:53248
	ds_read_b128 v[234:237], v192 offset:54272
	ds_read_b128 v[238:241], v192 offset:55296
	ds_read_b128 v[242:245], v192 offset:56320
	global_load_lds_dwordx4 v[138:139], off
	v_lshl_add_u64 v[138:139], v[194:195], 0, s[56:57]
	s_add_i32 m0, s5, 0x2000
	s_add_i32 s5, s62, s89
	global_load_lds_dwordx4 v[138:139], off
	v_lshl_add_u64 v[138:139], v[246:247], 0, s[56:57]
	s_mov_b32 m0, s5
	s_nop 0
	global_load_lds_dwordx4 v[138:139], off
	v_lshl_add_u64 v[138:139], v[248:249], 0, s[56:57]
	s_add_i32 m0, s5, 0x2000
	s_nop 0
	global_load_lds_dwordx4 v[138:139], off
	v_lshl_add_u64 v[138:139], v[250:251], 0, s[56:57]
	s_mov_b32 m0, s94
	s_nop 0
	global_load_lds_dwordx4 v[138:139], off
	v_lshl_add_u64 v[138:139], v[180:181], 0, s[56:57]
	s_mov_b32 m0, s95
	s_nop 0
	global_load_lds_dwordx4 v[138:139], off
	s_waitcnt vmcnt(8)
	s_waitcnt lgkmcnt(0)
	s_barrier
	s_setprio 1
	s_waitcnt lgkmcnt(0)
	v_mfma_f32_16x16x32_bf16 v[68:71], v[134:137], v[214:217], v[68:71]
	v_mfma_f32_16x16x32_bf16 v[68:71], v[158:161], v[218:221], v[68:71]
	v_mfma_f32_16x16x32_bf16 v[72:75], v[162:165], v[214:217], v[72:75]
	v_mfma_f32_16x16x32_bf16 v[72:75], v[166:169], v[218:221], v[72:75]
	v_mfma_f32_16x16x32_bf16 v[84:87], v[134:137], v[222:225], v[84:87]
	v_mfma_f32_16x16x32_bf16 v[84:87], v[158:161], v[226:229], v[84:87]
	v_mfma_f32_16x16x32_bf16 v[88:91], v[162:165], v[222:225], v[88:91]
	v_mfma_f32_16x16x32_bf16 v[88:91], v[166:169], v[226:229], v[88:91]
	v_mfma_f32_16x16x32_bf16 v[100:103], v[134:137], v[230:233], v[100:103]
	v_mfma_f32_16x16x32_bf16 v[100:103], v[158:161], v[234:237], v[100:103]
	v_mfma_f32_16x16x32_bf16 v[104:107], v[162:165], v[230:233], v[104:107]
	v_mfma_f32_16x16x32_bf16 v[104:107], v[166:169], v[234:237], v[104:107]
	v_mfma_f32_16x16x32_bf16 v[116:119], v[134:137], v[238:241], v[116:119]
	v_mfma_f32_16x16x32_bf16 v[116:119], v[158:161], v[242:245], v[116:119]
	v_mfma_f32_16x16x32_bf16 v[120:123], v[162:165], v[238:241], v[120:123]
	v_mfma_f32_16x16x32_bf16 v[120:123], v[166:169], v[242:245], v[120:123]
	s_setprio 0
	s_setprio 1
	v_mfma_f32_16x16x32_bf16 v[76:79], v[198:201], v[214:217], v[76:79]
	v_mfma_f32_16x16x32_bf16 v[76:79], v[202:205], v[218:221], v[76:79]
	v_mfma_f32_16x16x32_bf16 v[80:83], v[206:209], v[214:217], v[80:83]
	v_mfma_f32_16x16x32_bf16 v[80:83], v[210:213], v[218:221], v[80:83]
	v_mfma_f32_16x16x32_bf16 v[92:95], v[198:201], v[222:225], v[92:95]
	v_mfma_f32_16x16x32_bf16 v[92:95], v[202:205], v[226:229], v[92:95]
	v_mfma_f32_16x16x32_bf16 v[96:99], v[206:209], v[222:225], v[96:99]
	v_mfma_f32_16x16x32_bf16 v[96:99], v[210:213], v[226:229], v[96:99]
	v_mfma_f32_16x16x32_bf16 v[108:111], v[198:201], v[230:233], v[108:111]
	v_mfma_f32_16x16x32_bf16 v[108:111], v[202:205], v[234:237], v[108:111]
	v_mfma_f32_16x16x32_bf16 v[112:115], v[206:209], v[230:233], v[112:115]
	v_mfma_f32_16x16x32_bf16 v[112:115], v[210:213], v[234:237], v[112:115]
	v_mfma_f32_16x16x32_bf16 v[124:127], v[198:201], v[238:241], v[124:127]
	v_mfma_f32_16x16x32_bf16 v[124:127], v[202:205], v[242:245], v[124:127]
	v_mfma_f32_16x16x32_bf16 v[128:131], v[206:209], v[238:241], v[128:131]
	v_mfma_f32_16x16x32_bf16 v[128:131], v[210:213], v[242:245], v[128:131]
	s_setprio 0
	s_barrier
	s_add_u32 s12, s12, 0x100
	s_addc_u32 s13, s13, 0
	v_lshl_add_u64 v[132:133], v[132:133], 0, s[42:43]
	v_lshl_add_u64 v[2:3], v[2:3], 0, s[42:43]
	s_cmp_ge_u32 s4, s96
	s_mov_b32 s5, s4
	s_cbranch_scc0 .LBB0_230
	s_and_b64 vcc, exec, s[64:65]
	s_cbranch_vccz .LBB0_233
	s_barrier
